# indexer selection: (amax, amin) all-reduce via row-rotate DPP + readlane instead of six ds_bpermute round trips
# baseline (speedup 1.0000x reference)
; __device__ __forceinline__ void indexer_phase(const bf16_t* PJ, float* rk, unsigned short* SEL, LAS unsigned char* lds) {
;     ...
; #pragma unroll
;                 for (int o = 1; o < 64; o <<= 1) { amax = fmaxf(amax, __shfl_xor(amax, o)); amin = fminf(amin, __shfl_xor(amin, o)); }
;                 if (lev < 2 && !by_index) {
;                     if (lev == 0) { lo0 = lo; sc0 = sc; b0 = bstar; } else { lo1 = lo; sc1 = sc; b1 = bstar; }
;                     if (amax > amin) { lo = amin; sc = 511.f / (amax - amin); }
;                     else { by_index = true; lo = -(float)t; sc = 511.f / (float)t; }
.LBB0_926:
	s_cmp_lt_u32 s57, 2
	s_cselect_b64 s[26:27], -1, 0
	s_xor_b64 s[28:29], s[88:89], -1
	s_and_b64 s[26:27], s[26:27], s[28:29]
	s_nop 1
	v_max_f32_dpp v3, v7, v7 row_ror:8 row_mask:0xf bank_mask:0xf
	v_min_f32_dpp v5, v9, v9 row_ror:8 row_mask:0xf bank_mask:0xf
	s_nop 0
	v_max_f32_dpp v3, v3, v3 row_ror:4 row_mask:0xf bank_mask:0xf
	v_min_f32_dpp v5, v5, v5 row_ror:4 row_mask:0xf bank_mask:0xf
	s_nop 0
	v_max_f32_dpp v3, v3, v3 row_ror:2 row_mask:0xf bank_mask:0xf
	v_min_f32_dpp v5, v5, v5 row_ror:2 row_mask:0xf bank_mask:0xf
	s_nop 0
	v_max_f32_dpp v3, v3, v3 row_ror:1 row_mask:0xf bank_mask:0xf
	v_min_f32_dpp v5, v5, v5 row_ror:1 row_mask:0xf bank_mask:0xf
	s_nop 0
	v_readlane_b32 s28, v3, 0
	v_readlane_b32 s29, v3, 16
	v_readlane_b32 s34, v3, 32
	v_readlane_b32 s35, v3, 48
	s_nop 0
	v_mov_b32_e32 v1, s28
	v_max_f32_e32 v1, s29, v1
	v_max_f32_e32 v1, s34, v1
	v_max_f32_e32 v1, s35, v1
	v_readlane_b32 s28, v5, 0
	v_readlane_b32 s29, v5, 16
	v_readlane_b32 s34, v5, 32
	v_readlane_b32 s35, v5, 48
	s_nop 0
	v_mov_b32_e32 v0, s28
	v_min_f32_e32 v0, s29, v0
	v_min_f32_e32 v0, s34, v0
	v_min_f32_e32 v0, s35, v0
	s_and_saveexec_b64 s[28:29], s[26:27]
	s_xor_b64 s[26:27], exec, s[28:29]
	s_cbranch_execz .LBB0_928
	v_mov_b32_e32 v3, s59
	v_cndmask_b32_e64 v67, v3, v8, s[24:25]
	v_cndmask_b32_e64 v65, v10, v3, s[24:25]
	v_sub_f32_e32 v3, v1, v0
	v_cmp_ngt_f32_e64 s[34:35], v1, v0
	v_cndmask_b32_e64 v17, v6, v12, s[24:25]
	v_cndmask_b32_e64 v13, v4, v14, s[24:25]
	v_cndmask_b32_e64 v1, v3, v25, s[34:35]
	v_div_scale_f32 v5, s[28:29], v1, v1, s45
	v_rcp_f32_e32 v7, v5
	v_cndmask_b32_e64 v3, v0, v26, s[34:35]
	v_cndmask_b32_e64 v19, v16, v6, s[24:25]
	v_cndmask_b32_e64 v15, v18, v4, s[24:25]
	v_fma_f32 v0, -v5, v7, 1.0
	v_fmac_f32_e32 v7, v0, v7
	v_div_scale_f32 v0, vcc, s45, v1, s45
	v_mul_f32_e32 v9, v0, v7
	v_fma_f32 v66, -v5, v9, v0
	v_fmac_f32_e32 v9, v66, v7
	v_fma_f32 v0, -v5, v9, v0
	v_div_fmas_f32 v0, v0, v7, v9
	v_div_fixup_f32 v66, v0, v1, s45
